# differential-attention loop: only the in-place exp2 arguments packed (they sit in a VALU-only stretch); the row sums next to the MFMAs stay scalar, as the microarchitecture notes price packed f32 besi
# speedup vs baseline: 1.0025x; 1.0025x over previous
.LBB0_1089:
	v_cndmask_b32_e64 v193, v136, v140, s[4:5]
	v_mul_f32_e32 v194, 0xbe38aa3b, v193
	v_pk_fma_f32 v[80:81], v[80:81], s[44:45], v[194:195] op_sel_hi:[1,0,0]
	v_pk_fma_f32 v[82:83], v[82:83], s[44:45], v[194:195] op_sel_hi:[1,0,0]
	v_pk_fma_f32 v[84:85], v[84:85], s[44:45], v[194:195] op_sel_hi:[1,0,0]
	v_pk_fma_f32 v[86:87], v[86:87], s[44:45], v[194:195] op_sel_hi:[1,0,0]
	v_pk_fma_f32 v[88:89], v[88:89], s[44:45], v[194:195] op_sel_hi:[1,0,0]
	v_pk_fma_f32 v[90:91], v[90:91], s[44:45], v[194:195] op_sel_hi:[1,0,0]
	v_pk_fma_f32 v[92:93], v[92:93], s[44:45], v[194:195] op_sel_hi:[1,0,0]
	v_pk_fma_f32 v[94:95], v[94:95], s[44:45], v[194:195] op_sel_hi:[1,0,0]
	v_exp_f32_e32 v136, v80
	v_exp_f32_e32 v137, v81
	v_exp_f32_e32 v138, v82
	v_exp_f32_e32 v139, v83
	v_exp_f32_e32 v147, v84
	v_exp_f32_e32 v149, v85
	v_exp_f32_e32 v150, v86
	v_exp_f32_e32 v151, v87
	v_exp_f32_e32 v140, v88
	v_exp_f32_e32 v141, v89
	v_exp_f32_e32 v142, v90
	v_exp_f32_e32 v143, v91
	v_exp_f32_e32 v144, v92
	v_exp_f32_e32 v145, v93
	v_exp_f32_e32 v146, v94
	v_exp_f32_e32 v148, v95
	v_fmamk_f32 v203, v64, 0x3e38aa3b, v194
	v_fmamk_f32 v204, v65, 0x3e38aa3b, v194
	v_fmamk_f32 v205, v66, 0x3e38aa3b, v194
	v_fmamk_f32 v206, v67, 0x3e38aa3b, v194
	v_fmamk_f32 v207, v68, 0x3e38aa3b, v194
	v_fmamk_f32 v196, v69, 0x3e38aa3b, v194
	v_fmamk_f32 v197, v70, 0x3e38aa3b, v194
	v_fmamk_f32 v198, v71, 0x3e38aa3b, v194
	v_fmamk_f32 v199, v72, 0x3e38aa3b, v194
	v_fmamk_f32 v200, v73, 0x3e38aa3b, v194
	v_fmamk_f32 v201, v74, 0x3e38aa3b, v194
	v_fmamk_f32 v202, v75, 0x3e38aa3b, v194
	v_fmamk_f32 v195, v76, 0x3e38aa3b, v194
	v_fmamk_f32 v208, v77, 0x3e38aa3b, v194
	v_fmamk_f32 v209, v78, 0x3e38aa3b, v194
	v_fmac_f32_e32 v194, 0x3e38aa3b, v79
	s_waitcnt lgkmcnt(0)
	s_barrier
	ds_read_b128 v[64:67], v181 offset:32768
	ds_read_b128 v[68:71], v181 offset:36864
	ds_read_b128 v[210:213], v187 offset:32768
	ds_read_b128 v[232:235], v187 offset:36864
	v_exp_f32_e32 v203, v203
	v_exp_f32_e32 v204, v204
	s_waitcnt lgkmcnt(3)
	v_mfma_f32_32x32x16_bf16 v[80:95], v[64:67], v[108:111], 0
	v_exp_f32_e32 v205, v205
	v_exp_f32_e32 v206, v206
	v_exp_f32_e32 v207, v207
	v_exp_f32_e32 v196, v196
	v_exp_f32_e32 v197, v197
	v_exp_f32_e32 v198, v198
	v_exp_f32_e32 v199, v199
	s_waitcnt lgkmcnt(2)
	v_mfma_f32_32x32x16_bf16 v[64:79], v[68:71], v[108:111], 0
	v_exp_f32_e32 v200, v200
	v_exp_f32_e32 v201, v201
	v_exp_f32_e32 v202, v202
	v_exp_f32_e32 v208, v208
	v_exp_f32_e32 v209, v209
	s_waitcnt lgkmcnt(1)
	v_mfma_f32_32x32x16_bf16 v[80:95], v[210:213], v[100:103], v[80:95]
	s_waitcnt lgkmcnt(0)
	v_mfma_f32_32x32x16_bf16 v[64:79], v[232:235], v[100:103], v[64:79]
	ds_read_b128 v[210:213], v188 offset:32768
	ds_read_b128 v[232:235], v188 offset:36864
	s_waitcnt lgkmcnt(1)
	v_mfma_f32_32x32x16_bf16 v[80:95], v[210:213], v[96:99], v[80:95]
	s_waitcnt lgkmcnt(0)
	v_mfma_f32_32x32x16_bf16 v[64:79], v[232:235], v[96:99], v[64:79]
	ds_read_b128 v[210:213], v176 offset:32768
	ds_read_b128 v[232:235], v176 offset:36864
	s_waitcnt lgkmcnt(1)
	v_mfma_f32_32x32x16_bf16 v[80:95], v[210:213], v[104:107], v[80:95]
	v_exp_f32_e32 v211, v194
	v_add_f32_e32 v194, 0, v136
	v_add_f32_e32 v194, v137, v194
	v_add_f32_e32 v194, v138, v194
	v_add_f32_e32 v194, v139, v194
	v_add_f32_e32 v194, v147, v194
	v_add_f32_e32 v194, v149, v194
	v_add_f32_e32 v194, v150, v194
	v_add_f32_e32 v194, v151, v194
	v_add_f32_e32 v194, v140, v194
	v_add_f32_e32 v194, v141, v194
	v_add_f32_e32 v194, v142, v194
	v_add_f32_e32 v194, v143, v194
	v_add_f32_e32 v194, v144, v194
	v_add_f32_e32 v194, v145, v194
	v_add_f32_e32 v194, v146, v194
	v_add_f32_e32 v194, v148, v194
	v_add_f32_e32 v194, v203, v194
	v_add_f32_e32 v194, v204, v194
	v_add_f32_e32 v194, v205, v194
	v_add_f32_e32 v194, v206, v194
	v_add_f32_e32 v194, v207, v194
	v_add_f32_e32 v194, v196, v194
	v_add_f32_e32 v194, v197, v194
	v_add_f32_e32 v194, v198, v194
	v_exp_f32_e32 v210, v195
	v_add_f32_e32 v194, v199, v194
	v_add_f32_e32 v194, v200, v194
	s_waitcnt lgkmcnt(0)
	v_mfma_f32_32x32x16_bf16 v[64:79], v[232:235], v[104:107], v[64:79]
	v_add_f32_e32 v194, v201, v194
	v_add_f32_e32 v194, v202, v194
	v_add_f32_e32 v194, v210, v194
	v_add_f32_e32 v194, v208, v194
	v_add_f32_e32 v194, v209, v194
	v_add_f32_e32 v194, v211, v194
	v_mov_b32_e32 v195, v194
	v_cvt_pk_bf16_f32 v136, v136, v137
	v_cvt_pk_bf16_f32 v137, v138, v139
	v_cvt_pk_bf16_f32 v138, v147, v149
	v_cvt_pk_bf16_f32 v139, v150, v151
	v_cvt_pk_bf16_f32 v140, v140, v141
	v_cvt_pk_bf16_f32 v141, v142, v143
	v_cvt_pk_bf16_f32 v142, v144, v145
	v_cvt_pk_bf16_f32 v143, v146, v148
	v_cvt_pk_bf16_f32 v144, v203, v204
	v_cvt_pk_bf16_f32 v145, v205, v206
	v_cvt_pk_bf16_f32 v146, v207, v196
	v_cvt_pk_bf16_f32 v147, v197, v198
	v_cvt_pk_bf16_f32 v148, v199, v200
	v_cvt_pk_bf16_f32 v149, v201, v202
	v_cvt_pk_bf16_f32 v150, v210, v208
	v_cvt_pk_bf16_f32 v151, v209, v211
	v_permlane32_swap_b32_e32 v194, v195
	v_permlane32_swap_b32_e32 v136, v138
	v_permlane32_swap_b32_e32 v137, v139
	v_permlane32_swap_b32_e32 v140, v142
	v_permlane32_swap_b32_e32 v141, v143
	v_permlane32_swap_b32_e32 v144, v146
	v_permlane32_swap_b32_e32 v145, v147
	v_permlane32_swap_b32_e32 v148, v150
	v_permlane32_swap_b32_e32 v149, v151
	s_cmp_ge_u32 s46, s47
	s_cselect_b64 s[8:9], -1, 0
	s_and_b64 vcc, exec, s[8:9]
	s_cbranch_vccnz .LBB0_1091
	v_add_co_u32_e32 v112, vcc, 0x18700000, v160
	s_nop 1
	v_addc_co_u32_e32 v113, vcc, 0, v161, vcc
	v_add_co_u32_e32 v116, vcc, 0x18740000, v160
	s_nop 1
	v_addc_co_u32_e32 v117, vcc, 0, v161, vcc
	v_add_co_u32_e32 v120, vcc, 0x18700000, v162
	global_load_dwordx4 v[112:115], v[112:113], off offset:3072
	s_nop 0
	global_load_dwordx4 v[116:119], v[116:117], off offset:3072
	v_addc_co_u32_e32 v121, vcc, 0, v163, vcc
	global_load_dwordx4 v[120:123], v[120:121], off offset:1536
